# MoE-up tile prologue: the two row-list gathers issued together with one wait (were load-wait-load-wait)
# speedup vs baseline: 1.0029x; 1.0029x over previous
.LBB0_897:
	s_abs_i32 s3, s30
	s_mul_hi_u32 s12, s3, s29
	s_mul_i32 s13, s12, s26
	s_ashr_i32 s2, s30, 31
	s_sub_i32 s3, s3, s13
	s_xor_b32 s2, s2, s28
	s_add_i32 s13, s12, 1
	s_sub_i32 s14, s3, s26
	s_cmp_ge_u32 s3, s26
	s_cselect_b32 s12, s13, s12
	s_cselect_b32 s3, s14, s3
	s_add_i32 s13, s12, 1
	s_cmp_ge_u32 s3, s26
	s_cselect_b32 s3, s13, s12
	s_xor_b32 s3, s3, s2
	s_sub_i32 s2, s3, s2
	s_mul_i32 s3, s2, s19
	s_sub_i32 s3, s30, s3
	s_lshl_b32 s12, s3, 5
	v_mov_b32_e32 v181, v216
	s_and_b32 s31, s12, 0xffffff80
	s_lshl_b32 s3, s3, 8
	v_ashrrev_i32_e32 v2, 2, v181
	v_add_u32_e32 v3, s31, v2
	v_lshlrev_b32_e32 v0, 4, v181
	v_and_b32_e32 v4, 48, v0
	v_min_i32_e32 v0, s27, v3
	v_ashrrev_i32_e32 v1, 31, v0
	v_lshl_add_u64 v[0:1], v[0:1], 2, s[0:1]
	global_load_dword v0, v[0:1], off
	v_add_u32_e32 v6, 64, v3
	v_min_i32_e32 v6, s27, v6
	v_ashrrev_i32_e32 v7, 31, v6
	v_lshl_add_u64 v[6:7], v[6:7], 2, s[0:1]
	global_load_dword v6, v[6:7], off
	s_lshl_b32 s2, s2, 10
	s_and_b32 s3, s3, 0x300
	s_or_b32 s34, s3, s2
	v_and_b32_e32 v183, 31, v181
	s_mov_b32 s35, 0
	s_waitcnt vmcnt(0)
	v_lshlrev_b32_e32 v0, 10, v0
	v_and_or_b32 v180, v0, s83, v4
	v_lshlrev_b32_e32 v6, 10, v6
	v_and_or_b32 v182, v6, s83, v4
	v_add_u32_e32 v0, s34, v2
	v_lshl_or_b32 v178, v0, 11, v4
	v_add_u32_e32 v0, 0x20000, v178
	v_add_u32_e32 v1, 0x40000, v178
	v_add_u32_e32 v3, 0x60000, v178
	v_mul_lo_u32 v0, v2, s74
	v_add_u32_e32 v188, v4, v0
	v_or_b32_e32 v0, 64, v180
	v_lshl_add_u64 v[186:187], s[10:11], 0, v[178:179]
	s_waitcnt vmcnt(0)
	s_waitcnt vmcnt(0)
	s_waitcnt vmcnt(0)
	s_waitcnt vmcnt(0)
	s_waitcnt vmcnt(0)
	s_waitcnt vmcnt(0)
	v_or_b32_e32 v0, 64, v182
	v_add_u32_e32 v0, 0x20040, v178
	v_add_u32_e32 v0, 0x40040, v178
	v_add_u32_e32 v0, 0x60040, v178
	v_ashrrev_i32_e32 v0, 1, v181
	v_and_b32_e32 v189, 0xffffffc0, v0
	v_lshrrev_b32_e32 v0, 1, v181
	v_or_b32_e32 v1, v189, v183
	v_and_b32_e32 v0, 16, v0
	v_mad_u64_u32 v[184:185], s[2:3], v1, s74, v[0:1]
	v_lshlrev_b32_e32 v1, 1, v181
	v_and_b32_e32 v185, 0x80, v1
	v_or_b32_e32 v1, v185, v183
	v_mul_u32_u24_e32 v1, 40, v1
	v_lshl_add_u32 v190, v1, 1, v0
	v_mov_b32_e32 v0, 0
	s_mov_b64 s[2:3], 0
	v_mov_b32_e32 v1, v0
	v_mov_b32_e32 v2, v0
	v_mov_b32_e32 v3, v0
	v_mov_b32_e32 v4, v0
	v_mov_b32_e32 v5, v0
	v_mov_b32_e32 v6, v0
	v_mov_b32_e32 v7, v0
	v_mov_b32_e32 v8, v0
	v_mov_b32_e32 v9, v0
	v_mov_b32_e32 v10, v0
	v_mov_b32_e32 v11, v0
	v_mov_b32_e32 v12, v0
	v_mov_b32_e32 v13, v0
	v_mov_b32_e32 v14, v0
	v_mov_b32_e32 v15, v0
	v_mov_b32_e32 v16, v0
	v_mov_b32_e32 v17, v0
	v_mov_b32_e32 v18, v0
	v_mov_b32_e32 v19, v0
	v_mov_b32_e32 v20, v0
	v_mov_b32_e32 v21, v0
	v_mov_b32_e32 v22, v0
	v_mov_b32_e32 v23, v0
	v_mov_b32_e32 v24, v0
	v_mov_b32_e32 v25, v0
	v_mov_b32_e32 v26, v0
	v_mov_b32_e32 v27, v0
	v_mov_b32_e32 v28, v0
	v_mov_b32_e32 v29, v0
	v_mov_b32_e32 v30, v0
	v_mov_b32_e32 v31, v0
	v_mov_b32_e32 v64, v0
	v_mov_b32_e32 v65, v0
	v_mov_b32_e32 v66, v0
	v_mov_b32_e32 v67, v0
	v_mov_b32_e32 v68, v0
	v_mov_b32_e32 v69, v0
	v_mov_b32_e32 v70, v0
	v_mov_b32_e32 v71, v0
	v_mov_b32_e32 v72, v0
	v_mov_b32_e32 v73, v0
	v_mov_b32_e32 v74, v0
	v_mov_b32_e32 v75, v0
	v_mov_b32_e32 v76, v0
	v_mov_b32_e32 v77, v0
	v_mov_b32_e32 v78, v0
	v_mov_b32_e32 v79, v0
	v_mov_b32_e32 v80, v0
	v_mov_b32_e32 v81, v0
	v_mov_b32_e32 v82, v0
	v_mov_b32_e32 v83, v0
	v_mov_b32_e32 v84, v0
	v_mov_b32_e32 v85, v0
	v_mov_b32_e32 v86, v0
	v_mov_b32_e32 v87, v0
	v_mov_b32_e32 v88, v0
	v_mov_b32_e32 v89, v0
	v_mov_b32_e32 v90, v0
	v_mov_b32_e32 v91, v0
	v_mov_b32_e32 v92, v0
	v_mov_b32_e32 v93, v0
	v_mov_b32_e32 v94, v0
	v_mov_b32_e32 v95, v0
	v_mov_b32_e32 v32, v0
	v_mov_b32_e32 v33, v0
	v_mov_b32_e32 v34, v0
	v_mov_b32_e32 v35, v0
	v_mov_b32_e32 v36, v0
	v_mov_b32_e32 v37, v0
	v_mov_b32_e32 v38, v0
	v_mov_b32_e32 v39, v0
	v_mov_b32_e32 v40, v0
	v_mov_b32_e32 v41, v0
	v_mov_b32_e32 v42, v0
	v_mov_b32_e32 v43, v0
	v_mov_b32_e32 v44, v0
	v_mov_b32_e32 v45, v0
	v_mov_b32_e32 v46, v0
	v_mov_b32_e32 v47, v0
	v_mov_b32_e32 v48, v0
	v_mov_b32_e32 v49, v0
	v_mov_b32_e32 v50, v0
	v_mov_b32_e32 v51, v0
	v_mov_b32_e32 v52, v0
	v_mov_b32_e32 v53, v0
	v_mov_b32_e32 v54, v0
	v_mov_b32_e32 v55, v0
	v_mov_b32_e32 v56, v0
	v_mov_b32_e32 v57, v0
	v_mov_b32_e32 v58, v0
	v_mov_b32_e32 v59, v0
	v_mov_b32_e32 v60, v0
	v_mov_b32_e32 v61, v0
	v_mov_b32_e32 v62, v0
	v_mov_b32_e32 v63, v0
	v_mov_b32_e32 v96, v0
	v_mov_b32_e32 v97, v0
	v_mov_b32_e32 v98, v0
	v_mov_b32_e32 v99, v0
	v_mov_b32_e32 v100, v0
	v_mov_b32_e32 v101, v0
	v_mov_b32_e32 v102, v0
	v_mov_b32_e32 v103, v0
	v_mov_b32_e32 v104, v0
	v_mov_b32_e32 v105, v0
	v_mov_b32_e32 v106, v0
	v_mov_b32_e32 v107, v0
	v_mov_b32_e32 v108, v0
	v_mov_b32_e32 v109, v0
	v_mov_b32_e32 v110, v0
	v_mov_b32_e32 v111, v0
	v_mov_b32_e32 v112, v0
	v_mov_b32_e32 v113, v0
	v_mov_b32_e32 v114, v0
	v_mov_b32_e32 v115, v0
	v_mov_b32_e32 v116, v0
	v_mov_b32_e32 v117, v0
	v_mov_b32_e32 v118, v0
	v_mov_b32_e32 v119, v0
	v_mov_b32_e32 v120, v0
	v_mov_b32_e32 v121, v0
	v_mov_b32_e32 v122, v0
	v_mov_b32_e32 v123, v0
	v_mov_b32_e32 v124, v0
	v_mov_b32_e32 v125, v0
	v_mov_b32_e32 v126, v0
	v_mov_b32_e32 v127, v0
	v_and_b32_e32 v137, 3, v216
	v_bfe_u32 v138, v216, 4, 2
	v_xor_b32_e32 v138, v137, v138
	v_sub_u32_e32 v138, v138, v137
	v_lshlrev_b32_e32 v136, 4, v138
	v_lshrrev_b32_e32 v137, 6, v216
	v_lshlrev_b32_e32 v138, 10, v137
	v_and_b32_e32 v139, 31, v216
	v_bfe_u32 v140, v216, 5, 1
	v_readfirstlane_b32 s14, v138
	v_bfe_u32 v141, v139, 2, 2
	v_lshrrev_b32_e32 v142, 1, v137
	v_and_b32_e32 v143, 1, v137
	v_lshl_add_u32 v142, v142, 6, v139
	v_lshl_add_u32 v143, v143, 7, v139
	v_lshlrev_b32_e32 v142, 6, v142
	v_lshlrev_b32_e32 v143, 6, v143
	v_add_u32_e32 v143, 0x4000, v143
	v_or_b32_e32 v144, 0, v140
	v_xor_b32_e32 v144, v144, v141
	v_lshl_add_u32 v128, v144, 4, v142
	v_lshl_add_u32 v130, v144, 4, v143
	v_or_b32_e32 v144, 2, v140
	v_xor_b32_e32 v144, v144, v141
	v_lshl_add_u32 v129, v144, 4, v142
	v_lshl_add_u32 v131, v144, 4, v143
	v_add_u32_e32 v193, s2, v180
	v_add_u32_e32 v192, s2, v182
	v_add_u32_e32 v191, s2, v178
	v_add_u32_e32 v132, v193, v136
	v_add_u32_e32 v133, v192, v136
	v_add_u32_e32 v134, v191, v136
	s_add_u32 m0, s14, 0x0
	v_add_u32_e32 v135, 0x0, v132
	global_load_lds_dwordx4 v135, s[6:7]
	s_add_u32 m0, s14, 0x1000
	v_add_u32_e32 v135, 0x0, v133
	global_load_lds_dwordx4 v135, s[6:7]
	s_add_u32 m0, s14, 0x4000
	v_add_u32_e32 v135, 0x0, v134
	global_load_lds_dwordx4 v135, s[8:9]
	s_add_u32 m0, s14, 0x5000
	v_add_u32_e32 v135, 0x20000, v134
	global_load_lds_dwordx4 v135, s[8:9]
	s_add_u32 m0, s14, 0x6000
	v_add_u32_e32 v135, 0x40000, v134
	global_load_lds_dwordx4 v135, s[8:9]
	s_add_u32 m0, s14, 0x7000
	v_add_u32_e32 v135, 0x60000, v134
	global_load_lds_dwordx4 v135, s[8:9]
	s_waitcnt vmcnt(0) lgkmcnt(0)
	s_barrier
	s_branch .Ldmaq19167_loop
